# v89 plus the same LDS staging of conv weights/bias for m1
# speedup vs baseline: 1.0143x; 1.0018x over previous
.LBB0_284:
	s_or_b64 exec, exec, s[0:1]
	s_mov_b64 s[0:1], s[72:73]
	v_readlane_b32 s4, v254, 35
	v_readlane_b32 s2, v254, 60
	s_and_b64 vcc, exec, s[58:59]
	s_waitcnt lgkmcnt(0)
	s_barrier
	v_readlane_b32 s3, v254, 61
	s_cbranch_vccz .LBB0_305
	s_load_dwordx2 s[6:7], s[0:1], 0x88
	s_load_dwordx8 s[8:15], s[0:1], 0x48
	s_mov_b32 s26, s70
	s_waitcnt lgkmcnt(0)
	s_add_u32 s0, s6, 0xc000000
	s_addc_u32 s1, s7, 0
	s_add_u32 s22, s6, 0xe000000
	s_addc_u32 s23, s7, 0
	s_lshl_b32 s2, s4, 12
	s_ashr_i32 s3, s2, 31
	s_lshl_b64 s[2:3], s[2:3], 2
	s_add_u32 s2, s8, s2
	s_addc_u32 s3, s9, s3
	s_lshl_b32 s8, s4, 10
	s_ashr_i32 s9, s8, 31
	s_lshl_b64 s[8:9], s[8:9], 2
	s_add_u32 s8, s10, s8
	s_addc_u32 s9, s11, s9
	s_lshl_b32 s4, s4, 3
	s_ashr_i32 s5, s4, 31
	s_lshl_b64 s[4:5], s[4:5], 2
	s_add_u32 s10, s14, s4
	s_addc_u32 s11, s15, s5
	s_add_u32 s12, s12, s4
	s_addc_u32 s13, s13, s5
	s_add_u32 s14, s6, 0x18000000
	s_addc_u32 s15, s7, 0
	s_add_u32 s24, s6, 0x18100000
	s_addc_u32 s25, s7, 0
	v_readlane_b32 s4, v254, 31
	s_add_u32 s16, s6, s4
	v_readlane_b32 s4, v254, 32
	s_addc_u32 s17, s7, s4
	v_readlane_b32 s4, v254, 33
	s_mov_b32 s18, s4
	v_lshlrev_b32_e32 v0, 4, v194
	global_load_dwordx4 v[4:7], v0, s[2:3]
	s_add_u32 s90, s2, 0x2000
	s_addc_u32 s91, s3, 0
	global_load_dwordx4 v[8:11], v0, s[90:91]
	v_cmp_gt_u32_e32 vcc, 0x100, v194
	s_and_saveexec_b64 s[92:93], vcc
	global_load_dwordx4 v[12:15], v0, s[8:9]
	s_mov_b64 exec, s[92:93]
	v_add_u32_e32 v1, 0x1a000, v0
	s_waitcnt vmcnt(0)
	ds_write_b128 v1, v[4:7]
	ds_write_b128 v1, v[8:11] offset:8192
	s_and_saveexec_b64 s[92:93], vcc
	ds_write_b128 v1, v[12:15] offset:16384
	s_mov_b64 exec, s[92:93]
	s_waitcnt lgkmcnt(0)
	s_barrier
	s_branch .LBB0_288

.LBB0_288:
	s_ashr_i32 s4, s26, 10
	s_and_b32 s28, s26, 0x7f
	s_ashr_i32 s5, s4, 31
	v_mov_b32_e32 v15, v194
	s_lshl_b64 s[20:21], s[4:5], 13
	s_lshl_b32 s4, s28, 6
	s_bfe_u32 s29, s26, 0x30007
	v_and_b32_e32 v14, 63, v15
	v_readfirstlane_b32 s27, v15
	s_or_b32 s20, s20, s4
	v_lshrrev_b32_e32 v209, 3, v15
	v_and_b32_e32 v210, 7, v15
	v_lshlrev_b32_e32 v211, 4, v210
	v_lshl_or_b32 v190, v209, 15, v211
	v_lshl_or_b32 v192, v209, 11, v211
	v_add_u32_e32 v193, 0x1000, v192
	v_lshlrev_b32_e32 v208, 5, v210
	s_lshl_b32 s90, s29, 7
	s_or_b32 s90, s90, 0x400
	s_lshl_b64 s[52:53], s[20:21], 1
	s_add_u32 s52, s22, s52
	s_addc_u32 s53, s23, s53
	s_lshl_b32 s91, s90, 15
	s_add_u32 s52, s52, s91
	s_addc_u32 s53, s53, 0
	s_add_u32 s54, s52, 0x200000
	s_addc_u32 s55, s53, 0
	global_load_dwordx4 v[44:47], v190, s[52:53]
	global_load_dwordx4 v[48:51], v190, s[54:55]
	s_sub_u32 s92, s20, 3
	s_subb_u32 s93, s21, 0
	s_lshl_b64 s[92:93], s[92:93], 11
	s_add_u32 s92, s0, s92
	s_addc_u32 s93, s1, s93
	s_lshl_b32 s91, s29, 7
	s_add_u32 s92, s92, s91
	s_addc_u32 s93, s93, 0
	s_cmp_lg_u32 s28, 0
	s_cselect_b64 s[54:55], -1, 0
	v_cmp_lt_u32_e32 vcc, 2, v209
	s_or_b64 s[46:47], s[54:55], vcc
	v_cmp_lt_u32_e32 vcc, 1, v209
	s_or_b64 s[48:49], s[54:55], vcc
	v_cmp_lt_u32_e32 vcc, 0, v209
	s_or_b64 s[50:51], s[54:55], vcc
	s_mov_b64 s[96:97], exec
	s_and_b64 exec, s[96:97], s[46:47]
	global_load_dwordx4 v[80:83], v192, s[92:93] offset:1024
	s_and_b64 exec, s[96:97], s[48:49]
	global_load_dwordx4 v[92:95], v192, s[92:93] offset:3072
	s_and_b64 exec, s[96:97], s[50:51]
	global_load_dwordx4 v[104:107], v193, s[92:93] offset:1024
	s_mov_b64 exec, s[96:97]
	global_load_dwordx4 v[116:119], v193, s[92:93] offset:3072
	s_cmp_gt_u32 s27, 63
	v_cmp_gt_u32_e32 vcc, 16, v14
	s_cbranch_scc1 .LBB0_292
	v_or_b32_e32 v0, s20, v14
	v_mov_b32_e32 v1, s21
	v_lshlrev_b64 v[0:1], 6, v[0:1]
	v_lshl_add_u64 v[0:1], s[14:15], 0, v[0:1]
	s_lshl_b32 s86, s29, 2
	v_lshl_add_u64 v[0:1], v[0:1], 0, s[86:87]
	v_mov_b32_e32 v3, s86
	global_load_dword v2, v[0:1], off offset:32
	global_load_dword v4, v3, s[10:11]
	s_nop 0
	global_load_dword v0, v[0:1], off
	s_nop 0
	global_load_dword v1, v3, s[12:13]
	s_waitcnt vmcnt(2)
	v_add_f32_e32 v2, v2, v4
	s_waitcnt vmcnt(0)
	v_add_f32_e32 v0, v0, v1
	v_min_f32_e32 v1, 0, v2
	v_mul_f32_e64 v2, |v2|, s79
	v_exp_f32_e32 v4, v2
	s_nop 0
	v_add_f32_e32 v5, 1.0, v4
	v_add_f32_e32 v2, -1.0, v5
	v_sub_f32_e32 v3, v2, v5
	v_add_f32_e32 v3, 1.0, v3
	v_sub_f32_e32 v2, v4, v2
	v_add_f32_e32 v6, v2, v3
	v_frexp_mant_f32_e32 v2, v5
	v_cmp_gt_f32_e64 s[4:5], s85, v2
	v_cvt_f64_f32_e32 v[2:3], v5
	v_frexp_exp_i32_f64_e32 v2, v[2:3]
	v_subbrev_co_u32_e64 v2, s[4:5], 0, v2, s[4:5]
	v_sub_u32_e32 v3, 0, v2
	v_ldexp_f32 v5, v5, v3
	v_ldexp_f32 v3, v6, v3
	v_add_f32_e32 v6, -1.0, v5
	v_add_f32_e32 v7, 1.0, v6
	v_sub_f32_e32 v7, v5, v7
	v_add_f32_e32 v7, v3, v7
	v_add_f32_e32 v8, v6, v7
	v_sub_f32_e32 v6, v8, v6
	v_sub_f32_e32 v6, v7, v6
	v_add_f32_e32 v7, 1.0, v5
	v_add_f32_e32 v9, -1.0, v7
	v_sub_f32_e32 v5, v5, v9
	v_add_f32_e32 v3, v3, v5
	v_add_f32_e32 v5, v7, v3
	v_sub_f32_e32 v7, v5, v7
	v_sub_f32_e32 v3, v3, v7
	v_rcp_f32_e32 v7, v5
	v_cvt_f32_i32_e32 v2, v2
	s_mov_b32 s4, 0x3f317218
	v_mul_f32_e32 v9, v8, v7
	v_mul_f32_e32 v10, v5, v9
	v_fma_f32 v11, v9, v5, -v10
	v_fmac_f32_e32 v11, v9, v3
	v_add_f32_e32 v12, v10, v11
	v_sub_f32_e32 v13, v8, v12
	v_sub_f32_e32 v8, v8, v13
	v_sub_f32_e32 v10, v12, v10
	v_sub_f32_e32 v8, v8, v12
	v_add_f32_e32 v6, v6, v8
	v_sub_f32_e32 v8, v10, v11
	v_add_f32_e32 v6, v8, v6
	v_add_f32_e32 v8, v13, v6
	v_mul_f32_e32 v10, v7, v8
	v_mul_f32_e32 v11, v5, v10
	v_fma_f32 v5, v10, v5, -v11
	v_fmac_f32_e32 v5, v10, v3
	v_sub_f32_e32 v3, v13, v8
	v_add_f32_e32 v3, v6, v3
	v_add_f32_e32 v6, v11, v5
	v_sub_f32_e32 v12, v8, v6
	v_sub_f32_e32 v8, v8, v12
	v_sub_f32_e32 v11, v6, v11
	v_sub_f32_e32 v6, v8, v6
	v_add_f32_e32 v3, v3, v6
	v_sub_f32_e32 v5, v11, v5
	v_add_f32_e32 v3, v5, v3
	v_add_f32_e32 v5, v9, v10
	v_add_f32_e32 v3, v12, v3
	v_sub_f32_e32 v6, v5, v9
	v_mul_f32_e32 v3, v7, v3
	v_sub_f32_e32 v6, v10, v6
	v_add_f32_e32 v3, v6, v3
	v_mul_f32_e32 v9, 0x3f317218, v2
	v_add_f32_e32 v6, v5, v3
	v_fma_f32 v10, v2, s4, -v9
	v_mul_f32_e32 v7, v6, v6
	v_fmac_f32_e32 v10, 0xb102e308, v2
	v_sub_f32_e32 v2, v6, v5
	v_fmamk_f32 v8, v7, 0x3e9b6dac, v200
	v_sub_f32_e32 v2, v3, v2
	v_add_f32_e32 v3, v9, v10
	v_fmaak_f32 v8, v7, v8, 0x3f2aaada
	v_sub_f32_e32 v5, v3, v9
	v_ldexp_f32 v9, v6, 1
	v_mul_f32_e32 v6, v6, v7
	v_mul_f32_e32 v6, v6, v8
	v_add_f32_e32 v7, v9, v6
	v_sub_f32_e32 v8, v7, v9
	v_ldexp_f32 v2, v2, 1
	v_sub_f32_e32 v6, v6, v8
	v_add_f32_e32 v2, v2, v6
	v_add_f32_e32 v6, v7, v2
	v_sub_f32_e32 v7, v6, v7
	v_sub_f32_e32 v2, v2, v7
	v_add_f32_e32 v7, v3, v6
	v_sub_f32_e32 v8, v7, v3
	v_sub_f32_e32 v9, v7, v8
	v_sub_f32_e32 v5, v10, v5
	v_sub_f32_e32 v3, v3, v9
	v_sub_f32_e32 v6, v6, v8
	v_add_f32_e32 v3, v6, v3
	v_add_f32_e32 v6, v5, v2
	v_sub_f32_e32 v8, v6, v5
	v_sub_f32_e32 v9, v6, v8
	v_sub_f32_e32 v5, v5, v9
	v_sub_f32_e32 v2, v2, v8
	v_add_f32_e32 v3, v6, v3
	v_add_f32_e32 v2, v2, v5
	v_add_f32_e32 v5, v7, v3
	v_sub_f32_e32 v6, v5, v7
	v_sub_f32_e32 v3, v3, v6
	v_add_f32_e32 v2, v2, v3
	s_mov_b32 s4, 0x7f800000
	v_add_f32_e32 v2, v5, v2
	v_cmp_neq_f32_e64 s[4:5], s4, v4
	v_add_u32_e32 v3, -1, v201
	s_nop 0
	v_cndmask_b32_e64 v2, v202, v2, s[4:5]
	v_cmp_ngt_f32_e64 s[4:5], -1.0, v4
	s_nop 1
	v_cndmask_b32_e64 v2, v203, v2, s[4:5]
	v_cmp_neq_f32_e64 s[4:5], -1.0, v4
	s_nop 1
	v_cndmask_b32_e64 v2, v204, v2, s[4:5]
	s_mov_b32 s4, 0x33800000
	v_cmp_lt_f32_e64 s[4:5], |v4|, s4
	s_nop 1
	v_cndmask_b32_e64 v2, v2, v4, s[4:5]
	v_sub_f32_e32 v1, v1, v2
	v_mov_b32_e32 v4, v1
	s_nop 1
	v_add_f32_dpp v4, v1, v4 row_shr:1 row_mask:0xf bank_mask:0xf
	v_add_f32_dpp v4, v1, v4 row_shr:2 row_mask:0xf bank_mask:0xf
	v_add_f32_dpp v4, v1, v4 row_shr:3 row_mask:0xf bank_mask:0xf
	s_nop 1
	v_add_f32_dpp v4, v4, v4 row_shr:4 row_mask:0xf bank_mask:0xe
	s_nop 1
	v_add_f32_dpp v4, v4, v4 row_shr:8 row_mask:0xf bank_mask:0xc
	s_nop 1
	v_add_f32_dpp v4, v4, v4 row_bcast:15 row_mask:0xa bank_mask:0xf
	s_nop 1
	v_add_f32_dpp v4, v4, v4 row_bcast:31 row_mask:0xc bank_mask:0xf
	s_nop 0
	v_readlane_b32 s6, v4, 63
	s_nop 1
	v_mov_b32_e32 v1, s6
	v_sub_f32_e32 v2, v1, v4
	v_add_f32_e32 v2, v0, v2
	v_mov_b32_e32 v3, v2
	s_nop 1
	v_max_f32_dpp v3, v2, v3 row_shr:1 row_mask:0xf bank_mask:0xf
	v_max_f32_dpp v3, v2, v3 row_shr:2 row_mask:0xf bank_mask:0xf
	v_max_f32_dpp v3, v2, v3 row_shr:3 row_mask:0xf bank_mask:0xf
	s_nop 1
	v_max_f32_dpp v3, v3, v3 row_shr:4 row_mask:0xf bank_mask:0xe
	s_nop 1
	v_max_f32_dpp v3, v3, v3 row_shr:8 row_mask:0xf bank_mask:0xc
	s_nop 1
	v_max_f32_dpp v3, v3, v3 row_bcast:15 row_mask:0xa bank_mask:0xf
	s_nop 1
	v_max_f32_dpp v3, v3, v3 row_bcast:31 row_mask:0xc bank_mask:0xf
	s_nop 0
	v_readlane_b32 s7, v3, 63
	v_cmp_eq_u32_e64 s[4:5], 0, v14
	s_nop 1
	v_mov_b32_e32 v0, s7
	v_sub_f32_e32 v2, v2, v0
	v_mul_f32_e32 v2, 0x3fb8aa3b, v2
	v_exp_f32_e32 v2, v2
	v_lshl_add_u32 v3, v14, 2, 0
	ds_write_b32 v3, v2 offset:29952
	s_and_saveexec_b64 s[6:7], s[4:5]
	s_cbranch_execz .LBB0_291
	s_ashr_i32 s19, s18, 31
	s_lshl_b64 s[4:5], s[18:19], 2
	s_add_u32 s4, s24, s4
	s_addc_u32 s5, s25, s5
	global_store_dwordx2 v172, v[0:1], s[4:5]

.LBB0_292:
	s_lshl_b32 s91, s29, 8
	s_add_u32 s91, s91, 0x1a000
	v_add_u32_e32 v191, s91, v208
	ds_read_b128 v[72:75], v191 offset:18432
	ds_read_b128 v[76:79], v191 offset:18448
	ds_read_b128 v[84:87], v191 offset:2048
	ds_read_b128 v[88:91], v191 offset:2064
	ds_read_b128 v[96:99], v191 offset:6144
	ds_read_b128 v[100:103], v191 offset:6160
	ds_read_b128 v[108:111], v191 offset:10240
	ds_read_b128 v[112:115], v191 offset:10256
	ds_read_b128 v[120:123], v191 offset:14336
	ds_read_b128 v[124:127], v191 offset:14352
	v_lshrrev_b32_e32 v8, 3, v15
	v_and_b32_e32 v16, 7, v15
	v_lshlrev_b32_e32 v16, 3, v16
	v_mul_u32_u24_e32 v24, 0x90, v8
	v_lshl_add_u32 v24, v16, 1, v24
	s_waitcnt vmcnt(0)
	ds_write_b128 v24, v[44:47] offset:9216
	ds_write_b128 v24, v[48:51] offset:18432
	v_cmp_gt_i32_e32 vcc, s66, v15
	s_and_saveexec_b64 s[4:5], vcc
	v_cmp_gt_u32_e32 vcc, 8, v15
	s_nop 1
	v_cndmask_b32_e32 v2, 0, v205, vcc
	v_mov_b32_e32 v3, v2
	v_mov_b32_e32 v4, v2
	v_mov_b32_e32 v5, v2
	ds_write_b128 v24, v[2:5] offset:27648
	s_or_b64 exec, exec, s[4:5]
	s_waitcnt lgkmcnt(0)
	v_mov_b32_e32 v4, v72
	v_mov_b32_e32 v5, v73
	v_mov_b32_e32 v6, v74
	v_mov_b32_e32 v7, v75
	v_mov_b32_e32 v0, v76
	v_mov_b32_e32 v1, v77
	v_mov_b32_e32 v2, v78
	v_mov_b32_e32 v3, v79
	s_and_saveexec_b64 s[4:5], s[46:47]
	v_lshlrev_b32_e32 v32, 16, v80
	v_and_b32_e32 v33, 0xffff0000, v80
	v_pk_fma_f32 v[4:5], v[84:85], v[32:33], v[4:5]
	v_lshlrev_b32_e32 v34, 16, v81
	v_and_b32_e32 v35, 0xffff0000, v81
	v_pk_fma_f32 v[6:7], v[86:87], v[34:35], v[6:7]
	v_lshlrev_b32_e32 v32, 16, v82
	v_and_b32_e32 v33, 0xffff0000, v82
	v_pk_fma_f32 v[0:1], v[88:89], v[32:33], v[0:1]
	v_lshlrev_b32_e32 v34, 16, v83
	v_and_b32_e32 v35, 0xffff0000, v83
	v_pk_fma_f32 v[2:3], v[90:91], v[34:35], v[2:3]
	s_or_b64 exec, exec, s[4:5]
	s_and_saveexec_b64 s[4:5], s[48:49]
	v_lshlrev_b32_e32 v32, 16, v92
	v_and_b32_e32 v33, 0xffff0000, v92
	v_pk_fma_f32 v[4:5], v[96:97], v[32:33], v[4:5]
	v_lshlrev_b32_e32 v34, 16, v93
	v_and_b32_e32 v35, 0xffff0000, v93
	v_pk_fma_f32 v[6:7], v[98:99], v[34:35], v[6:7]
	v_lshlrev_b32_e32 v32, 16, v94
	v_and_b32_e32 v33, 0xffff0000, v94
	v_pk_fma_f32 v[0:1], v[100:101], v[32:33], v[0:1]
	v_lshlrev_b32_e32 v34, 16, v95
	v_and_b32_e32 v35, 0xffff0000, v95
	v_pk_fma_f32 v[2:3], v[102:103], v[34:35], v[2:3]
	s_or_b64 exec, exec, s[4:5]
	s_and_saveexec_b64 s[4:5], s[50:51]
	v_lshlrev_b32_e32 v32, 16, v104
	v_and_b32_e32 v33, 0xffff0000, v104
	v_pk_fma_f32 v[4:5], v[108:109], v[32:33], v[4:5]
	v_lshlrev_b32_e32 v34, 16, v105
	v_and_b32_e32 v35, 0xffff0000, v105
	v_pk_fma_f32 v[6:7], v[110:111], v[34:35], v[6:7]
	v_lshlrev_b32_e32 v32, 16, v106
	v_and_b32_e32 v33, 0xffff0000, v106
	v_pk_fma_f32 v[0:1], v[112:113], v[32:33], v[0:1]
	v_lshlrev_b32_e32 v34, 16, v107
	v_and_b32_e32 v35, 0xffff0000, v107
	v_pk_fma_f32 v[2:3], v[114:115], v[34:35], v[2:3]
	s_or_b64 exec, exec, s[4:5]
	v_lshlrev_b32_e32 v32, 16, v116
	v_and_b32_e32 v33, 0xffff0000, v116
	v_pk_fma_f32 v[4:5], v[120:121], v[32:33], v[4:5]
	v_lshlrev_b32_e32 v34, 16, v117
	v_and_b32_e32 v35, 0xffff0000, v117
	v_pk_fma_f32 v[6:7], v[122:123], v[34:35], v[6:7]
	v_lshlrev_b32_e32 v32, 16, v118
	v_and_b32_e32 v33, 0xffff0000, v118
	v_pk_fma_f32 v[0:1], v[124:125], v[32:33], v[0:1]
	v_lshlrev_b32_e32 v34, 16, v119
	v_and_b32_e32 v35, 0xffff0000, v119
	v_pk_fma_f32 v[2:3], v[126:127], v[34:35], v[2:3]
	s_waitcnt vmcnt(0)
	v_mul_f32_e32 v11, 0xbfb8aa3b, v4
	v_exp_f32_e32 v11, v11
	s_waitcnt lgkmcnt(0)
	s_barrier
	v_add_f32_e32 v11, 1.0, v11
	v_rcp_f32_e32 v11, v11
	s_movk_i32 s19, 0x7fff
	v_and_b32_e32 v9, 15, v15
	s_lshr_b32 s4, s27, 2
	v_mul_f32_e32 v4, v4, v11
	v_mul_f32_e32 v11, 0xbfb8aa3b, v5
	v_exp_f32_e32 v11, v11
	v_lshrrev_b32_e32 v10, 4, v14
	v_lshlrev_b32_e32 v24, 2, v10
	v_add_f32_e32 v11, 1.0, v11
	v_rcp_f32_e32 v11, v11
	s_nop 0
	v_mul_f32_e32 v5, v5, v11
	v_mul_f32_e32 v11, 0xbfb8aa3b, v6
	v_exp_f32_e32 v11, v11
	s_nop 0
	v_add_f32_e32 v11, 1.0, v11
	v_rcp_f32_e32 v11, v11
	s_nop 0
	v_mul_f32_e32 v6, v6, v11
	v_mul_f32_e32 v11, 0xbfb8aa3b, v7
	v_exp_f32_e32 v11, v11
	s_nop 0
	v_add_f32_e32 v11, 1.0, v11
	v_rcp_f32_e32 v11, v11
	s_nop 0
	v_mul_f32_e32 v7, v7, v11
	v_mul_f32_e32 v11, 0xbfb8aa3b, v0
	v_exp_f32_e32 v11, v11
	s_nop 0
	v_add_f32_e32 v11, 1.0, v11
	v_rcp_f32_e32 v11, v11
	s_nop 0
	v_mul_f32_e32 v0, v0, v11
	v_mul_f32_e32 v11, 0xbfb8aa3b, v1
	v_exp_f32_e32 v11, v11
	s_nop 0
	v_add_f32_e32 v11, 1.0, v11
	v_rcp_f32_e32 v11, v11
	s_nop 0
	v_mul_f32_e32 v1, v1, v11
	v_mul_f32_e32 v11, 0xbfb8aa3b, v2
	v_exp_f32_e32 v11, v11
	s_nop 0
	v_add_f32_e32 v11, 1.0, v11
	v_rcp_f32_e32 v11, v11
	s_nop 0
	v_mul_f32_e32 v2, v2, v11
	v_mul_f32_e32 v11, 0xbfb8aa3b, v3
	v_exp_f32_e32 v11, v11
	s_nop 0
	v_add_f32_e32 v11, 1.0, v11
	v_rcp_f32_e32 v11, v11
	s_nop 0
	v_mul_f32_e32 v3, v3, v11
	v_lshl_add_u32 v11, v8, 2, 0
	ds_read_b32 v12, v11 offset:29952
	v_lshlrev_b32_e32 v8, 1, v8
	v_sub_u32_e32 v8, v11, v8
	v_mad_u32_u24 v8, v16, s84, v8
	s_waitcnt lgkmcnt(0)
	v_mul_f32_e32 v4, v12, v4
	v_bfe_u32 v11, v4, 16, 1
	v_add3_u32 v4, v4, v11, s19
	ds_write_b16_d16_hi v8, v4
	v_mul_f32_e32 v4, v12, v5
	v_bfe_u32 v5, v4, 16, 1
	v_add3_u32 v4, v4, v5, s19
	ds_write_b16_d16_hi v8, v4 offset:144
	v_mul_f32_e32 v4, v12, v6
	v_bfe_u32 v5, v4, 16, 1
	v_add3_u32 v4, v4, v5, s19
	ds_write_b16_d16_hi v8, v4 offset:288
	v_mul_f32_e32 v4, v12, v7
	v_bfe_u32 v5, v4, 16, 1
	v_add3_u32 v4, v4, v5, s19
	v_mul_f32_e32 v0, v12, v0
	ds_write_b16_d16_hi v8, v4 offset:432
	v_bfe_u32 v4, v0, 16, 1
	v_add3_u32 v0, v0, v4, s19
	ds_write_b16_d16_hi v8, v0 offset:576
	v_mul_f32_e32 v0, v12, v1
	v_bfe_u32 v1, v0, 16, 1
	v_add3_u32 v0, v0, v1, s19
	ds_write_b16_d16_hi v8, v0 offset:720
	v_mul_f32_e32 v0, v12, v2
	v_bfe_u32 v1, v0, 16, 1
	v_add3_u32 v0, v0, v1, s19
	ds_write_b16_d16_hi v8, v0 offset:864
	v_mul_f32_e32 v0, v12, v3
	v_bfe_u32 v1, v0, 16, 1
	v_add3_u32 v0, v0, v1, s19
	v_and_or_b32 v11, s4, 48, v9
	s_ashr_i32 s4, s27, 2
	ds_write_b16_d16_hi v8, v0 offset:1008
	v_and_b32_e32 v0, 48, v14
	s_andn2_b32 s4, s4, 63
	v_add_u32_e32 v8, 0, v0
	v_or_b32_e32 v0, s4, v9
	v_mad_u64_u32 v[12:13], s[6:7], v0, s84, v[8:9]
	s_waitcnt lgkmcnt(0)
	s_barrier
	v_mad_u32_u24 v15, v11, s84, v8
	ds_read_b128 v[4:7], v12 offset:9216
	ds_read_b128 v[0:3], v15
	s_waitcnt lgkmcnt(0)
	v_mfma_f32_16x16x32_bf16 v[16:19], v[4:7], v[0:3], 0
	ds_read_b128 v[20:23], v12 offset:9280
	ds_read_b128 v[4:7], v15 offset:64
	v_or_b32_e32 v12, s4, v24
	v_lshl_or_b32 v12, v12, 6, v11
	s_waitcnt lgkmcnt(0)
	v_mfma_f32_16x16x32_bf16 v[16:19], v[20:23], v[4:7], v[16:19]
	s_or_b32 s5, s4, 16
	s_nop 6
	v_bfe_u32 v13, v16, 16, 1
	v_add3_u32 v15, v16, v13, s19
	v_ashrrev_i32_e32 v13, 31, v12
	v_lshl_add_u64 v[12:13], v[12:13], 1, s[16:17]
	global_store_short_d16_hi v[12:13], v15, off
	v_bfe_u32 v15, v17, 16, 1
	v_add3_u32 v15, v17, v15, s19
	global_store_short_d16_hi v[12:13], v15, off offset:128
	v_bfe_u32 v15, v18, 16, 1
	v_add3_u32 v15, v18, v15, s19
	global_store_short_d16_hi v[12:13], v15, off offset:256
	v_bfe_u32 v15, v19, 16, 1
	v_add3_u32 v15, v19, v15, s19
	global_store_short_d16_hi v[12:13], v15, off offset:384
	v_or_b32_e32 v12, s5, v9
	v_mad_u64_u32 v[12:13], s[6:7], v12, s84, v[8:9]
	ds_read_b128 v[16:19], v12 offset:9216
	ds_read_b128 v[20:23], v12 offset:9280
	s_waitcnt lgkmcnt(1)
	v_mfma_f32_16x16x32_bf16 v[16:19], v[16:19], v[0:3], 0
	v_or_b32_e32 v12, s5, v24
	v_lshl_or_b32 v12, v12, 6, v11
	s_or_b32 s5, s4, 32
	s_waitcnt lgkmcnt(0)
	v_mfma_f32_16x16x32_bf16 v[16:19], v[20:23], v[4:7], v[16:19]
	s_nop 7
	v_bfe_u32 v13, v16, 16, 1
	v_add3_u32 v15, v16, v13, s19
	v_ashrrev_i32_e32 v13, 31, v12
	v_lshl_add_u64 v[12:13], v[12:13], 1, s[16:17]
	global_store_short_d16_hi v[12:13], v15, off
	v_bfe_u32 v15, v17, 16, 1
	v_add3_u32 v15, v17, v15, s19
	global_store_short_d16_hi v[12:13], v15, off offset:128
	v_bfe_u32 v15, v18, 16, 1
	v_add3_u32 v15, v18, v15, s19
	global_store_short_d16_hi v[12:13], v15, off offset:256
	v_bfe_u32 v15, v19, 16, 1
	v_add3_u32 v15, v19, v15, s19
	global_store_short_d16_hi v[12:13], v15, off offset:384
	v_or_b32_e32 v12, s5, v9
	v_mad_u64_u32 v[12:13], s[6:7], v12, s84, v[8:9]
	ds_read_b128 v[16:19], v12 offset:9216
	ds_read_b128 v[20:23], v12 offset:9280
	s_waitcnt lgkmcnt(1)
	v_mfma_f32_16x16x32_bf16 v[16:19], v[16:19], v[0:3], 0
	v_or_b32_e32 v12, s5, v24
	v_lshl_or_b32 v12, v12, 6, v11
	s_or_b32 s6, s4, 48
	s_waitcnt lgkmcnt(0)
	v_mfma_f32_16x16x32_bf16 v[16:19], v[20:23], v[4:7], v[16:19]
	s_cmpk_gt_u32 s27, 0xff
	s_nop 6
	v_bfe_u32 v13, v16, 16, 1
	v_add3_u32 v15, v16, v13, s19
	v_ashrrev_i32_e32 v13, 31, v12
	v_lshl_add_u64 v[12:13], v[12:13], 1, s[16:17]
	global_store_short_d16_hi v[12:13], v15, off
	v_bfe_u32 v15, v17, 16, 1
	v_add3_u32 v15, v17, v15, s19
	global_store_short_d16_hi v[12:13], v15, off offset:128
	v_bfe_u32 v15, v18, 16, 1
	v_add3_u32 v15, v18, v15, s19
	global_store_short_d16_hi v[12:13], v15, off offset:256
	v_bfe_u32 v15, v19, 16, 1
	v_add3_u32 v15, v19, v15, s19
	global_store_short_d16_hi v[12:13], v15, off offset:384
	v_or_b32_e32 v12, s6, v9
	v_mad_u64_u32 v[12:13], s[4:5], v12, s84, v[8:9]
	ds_read_b128 v[16:19], v12 offset:9216
	ds_read_b128 v[20:23], v12 offset:9280
	s_waitcnt lgkmcnt(1)
	v_mfma_f32_16x16x32_bf16 v[16:19], v[16:19], v[0:3], 0
	v_or_b32_e32 v8, s6, v24
	s_waitcnt lgkmcnt(0)
	v_mfma_f32_16x16x32_bf16 v[16:19], v[20:23], v[4:7], v[16:19]
	s_nop 7
	v_bfe_u32 v12, v16, 16, 1
	v_add3_u32 v15, v16, v12, s19
	v_lshl_or_b32 v12, v8, 6, v11
	v_ashrrev_i32_e32 v13, 31, v12
	v_bfe_u32 v8, v17, 16, 1
	v_lshl_add_u64 v[12:13], v[12:13], 1, s[16:17]
	v_add3_u32 v8, v17, v8, s19
	global_store_short_d16_hi v[12:13], v8, off offset:128
	v_bfe_u32 v8, v18, 16, 1
	v_add3_u32 v8, v18, v8, s19
	global_store_short_d16_hi v[12:13], v8, off offset:256
	v_bfe_u32 v8, v19, 16, 1
	v_add3_u32 v8, v19, v8, s19
	global_store_short_d16_hi v[12:13], v15, off
	global_store_short_d16_hi v[12:13], v8, off offset:384
	s_cbranch_scc1 .LBB0_287
	v_lshlrev_b32_e32 v8, 3, v10
	v_mul_u32_u24_e32 v9, 0x90, v9
	v_lshlrev_b32_e32 v8, 1, v8
	v_add3_u32 v8, 0, v9, v8
	ds_read_b128 v[16:19], v8 offset:27648
	v_cmp_gt_u32_e32 vcc, 16, v14
	s_waitcnt lgkmcnt(0)
	v_mfma_f32_16x16x32_bf16 v[0:3], v[16:19], v[0:3], 0
	ds_read_b128 v[16:19], v8 offset:27712
	s_waitcnt lgkmcnt(0)
	v_mfma_f32_16x16x32_bf16 v[0:3], v[16:19], v[4:7], v[0:3]
	s_and_saveexec_b64 s[4:5], vcc
	s_cbranch_execz .LBB0_286
	s_nop 5
	v_bfe_u32 v1, v0, 16, 1
	s_movk_i32 s6, 0x7fff
	v_add3_u32 v2, v0, v1, s6
	v_lshlrev_b32_e32 v0, 1, v11
	v_mov_b32_e32 v1, v172
	v_lshl_add_u64 v[0:1], s[16:17], 0, v[0:1]
	v_add_co_u32_e32 v0, vcc, 0x4000, v0
	s_nop 1
	v_addc_co_u32_e32 v1, vcc, 0, v1, vcc
	global_store_short_d16_hi v[0:1], v2, off
	s_branch .LBB0_286
